# NSA block-score summation: the 8 per-head LDS reads issued together with counted lgkmcnt waits (same fixed summation order)
# speedup vs baseline: 1.0057x; 1.0057x over previous
; #define LAS __attribute__((address_space(3)))
; DI void nsa_unit(const Params& p, lds8* lds, int bl, int g, int qb32) {
;     ...
;   { const LAS float* iw = (const LAS float*)(lds + NS_IMPW);
;     for (int idx = tid; idx < 32 * 32; idx += 512) { const int qq = idx >> 5, s = idx & 31; float a = 0.f;
; #pragma unroll
;       for (int w = 0; w < 8; ++w) a += iw[(w * 32 + qq) * 33 + s];
;       if (s == 0 || s == blk || s == blk - 1) a = 1e9f;
;       score[qq * 33 + s] = a; } }
.LBB0_907:
	v_ashrrev_i32_e32 v51, 5, v50
	v_mul_lo_u32 v51, v51, s1
	v_add_u32_e32 v55, v48, v51
	v_add_u32_e32 v56, 0xd800, v55
	ds_read_b32 v57, v55 offset:55296
	ds_read_b32 v58, v55 offset:59520
	ds_read_b32 v160, v55 offset:63744
	ds_read_b32 v161, v56 offset:12672
	ds_read_b32 v162, v56 offset:16896
	ds_read_b32 v163, v56 offset:21120
	ds_read_b32 v164, v56 offset:25344
	ds_read_b32 v165, v56 offset:29568
	v_add_u32_e32 v51, v49, v51
	v_cmp_lt_i32_e64 s[8:9], s95, v50
	s_or_b64 s[12:13], s[8:9], s[12:13]
	s_waitcnt lgkmcnt(7)
	v_add_f32_e32 v57, 0, v57
	s_waitcnt lgkmcnt(6)
	v_add_f32_e32 v57, v57, v58
	s_waitcnt lgkmcnt(5)
	v_add_f32_e32 v55, v57, v160
	s_waitcnt lgkmcnt(4)
	v_add_f32_e32 v55, v55, v161
	s_waitcnt lgkmcnt(3)
	v_add_f32_e32 v55, v55, v162
	s_waitcnt lgkmcnt(2)
	v_add_f32_e32 v55, v55, v163
	s_waitcnt lgkmcnt(1)
	v_add_f32_e32 v55, v55, v164
	s_waitcnt lgkmcnt(0)
	v_add_f32_e32 v55, v55, v165
	v_mov_b32_e32 v56, 0x4e6e6b28
	v_cndmask_b32_e32 v55, v55, v56, vcc
	ds_write_b32 v51, v55
	v_add_u32_e32 v51, 0x200, v50
	v_mov_b32_e32 v50, v51
	s_andn2_b64 exec, exec, s[12:13]
	s_cbranch_execnz .LBB0_907
